# gates GEMM epilogue rewritten: all Y loads issued up front, lazy per-unit sigmoid/silu math (same ops), saddr addressing
# speedup vs baseline: 1.0111x; 1.0094x over previous
.Lw4_nowait:
	v_lshl_add_u32 v156, s26, 8, v166
	s_cmp_gt_i32 s20, 5
	s_cbranch_scc1 .LBB0_1465
	s_branch .LBB0_1466

.LBB0_1465:
	v_or_b32_e32 v0, 0xfffffd00, v168
	v_lshl_add_u32 v0, s20, 7, v0
	v_lshlrev_b32_e32 v0, 1, v0
	v_lshl_add_u32 v134, v156, 10, v0
	v_add_u32_e32 v135, 0x4000, v134
	v_add_u32_e32 v136, 0x8000, v134
	v_add_u32_e32 v137, 0xc000, v134
	v_add_u32_e32 v158, 0x20000, v134
	v_add_u32_e32 v159, 0x24000, v134
	v_add_u32_e32 v160, 0x28000, v134
	v_add_u32_e32 v161, 0x2c000, v134
	global_load_dwordx4 v[170:173], v134, s[8:9]
	global_load_dwordx4 v[174:177], v135, s[8:9]
	global_load_dwordx4 v[178:181], v136, s[8:9]
	global_load_dwordx4 v[182:185], v137, s[8:9]
	global_load_dwordx4 v[186:189], v158, s[8:9]
	global_load_dwordx4 v[190:193], v159, s[8:9]
	global_load_dwordx4 v[194:197], v160, s[8:9]
	global_load_dwordx4 v[198:201], v161, s[8:9]
	v_mul_f32_e32 v224, 0xbfb8aa3b, v126
	v_mul_f32_e32 v225, 0xbfb8aa3b, v127
	v_mul_f32_e32 v226, 0xbfb8aa3b, v128
	v_mul_f32_e32 v227, 0xbfb8aa3b, v129
	v_mul_f32_e32 v228, 0xbfb8aa3b, v122
	v_mul_f32_e32 v229, 0xbfb8aa3b, v123
	v_mul_f32_e32 v230, 0xbfb8aa3b, v124
	v_mul_f32_e32 v231, 0xbfb8aa3b, v125
	v_mul_f32_e32 v232, 0xbfb8aa3b, v118
	v_mul_f32_e32 v233, 0xbfb8aa3b, v119
	v_mul_f32_e32 v234, 0xbfb8aa3b, v120
	v_mul_f32_e32 v235, 0xbfb8aa3b, v121
	v_mul_f32_e32 v236, 0xbfb8aa3b, v114
	v_mul_f32_e32 v237, 0xbfb8aa3b, v115
	v_mul_f32_e32 v238, 0xbfb8aa3b, v116
	v_mul_f32_e32 v239, 0xbfb8aa3b, v117
	v_exp_f32_e32 v224, v224
	v_exp_f32_e32 v225, v225
	v_exp_f32_e32 v226, v226
	v_exp_f32_e32 v227, v227
	v_exp_f32_e32 v228, v228
	v_exp_f32_e32 v229, v229
	v_exp_f32_e32 v230, v230
	v_exp_f32_e32 v231, v231
	v_exp_f32_e32 v232, v232
	v_exp_f32_e32 v233, v233
	v_exp_f32_e32 v234, v234
	v_exp_f32_e32 v235, v235
	v_exp_f32_e32 v236, v236
	v_exp_f32_e32 v237, v237
	v_exp_f32_e32 v238, v238
	v_exp_f32_e32 v239, v239
	v_add_f32_e32 v224, 1.0, v224
	v_add_f32_e32 v225, 1.0, v225
	v_add_f32_e32 v226, 1.0, v226
	v_add_f32_e32 v227, 1.0, v227
	v_add_f32_e32 v228, 1.0, v228
	v_add_f32_e32 v229, 1.0, v229
	v_add_f32_e32 v230, 1.0, v230
	v_add_f32_e32 v231, 1.0, v231
	v_add_f32_e32 v232, 1.0, v232
	v_add_f32_e32 v233, 1.0, v233
	v_add_f32_e32 v234, 1.0, v234
	v_add_f32_e32 v235, 1.0, v235
	v_add_f32_e32 v236, 1.0, v236
	v_add_f32_e32 v237, 1.0, v237
	v_add_f32_e32 v238, 1.0, v238
	v_add_f32_e32 v239, 1.0, v239
	v_rcp_f32_e32 v224, v224
	v_rcp_f32_e32 v225, v225
	v_rcp_f32_e32 v226, v226
	v_rcp_f32_e32 v227, v227
	v_rcp_f32_e32 v228, v228
	v_rcp_f32_e32 v229, v229
	v_rcp_f32_e32 v230, v230
	v_rcp_f32_e32 v231, v231
	v_rcp_f32_e32 v232, v232
	v_rcp_f32_e32 v233, v233
	v_rcp_f32_e32 v234, v234
	v_rcp_f32_e32 v235, v235
	v_rcp_f32_e32 v236, v236
	v_rcp_f32_e32 v237, v237
	v_rcp_f32_e32 v238, v238
	v_rcp_f32_e32 v239, v239
	v_mul_f32_e32 v118, v118, v232
	v_mul_f32_e32 v119, v119, v233
	v_mul_f32_e32 v120, v120, v234
	v_mul_f32_e32 v121, v121, v235
	v_mul_f32_e32 v114, v114, v236
	v_mul_f32_e32 v115, v115, v237
	v_mul_f32_e32 v116, v116, v238
	v_mul_f32_e32 v117, v117, v239
	s_waitcnt vmcnt(7)
	v_lshlrev_b32_e32 v232, 16, v170
	v_and_b32_e32 v233, 0xffff0000, v170
	v_lshlrev_b32_e32 v234, 16, v171
	v_and_b32_e32 v235, 0xffff0000, v171
	v_lshlrev_b32_e32 v236, 16, v172
	v_and_b32_e32 v237, 0xffff0000, v172
	v_lshlrev_b32_e32 v238, 16, v173
	v_and_b32_e32 v239, 0xffff0000, v173
	v_mul_f32_e32 v224, v224, v232
	v_mul_f32_e32 v225, v225, v233
	v_mul_f32_e32 v226, v226, v234
	v_mul_f32_e32 v227, v227, v235
	v_mul_f32_e32 v228, v228, v236
	v_mul_f32_e32 v229, v229, v237
	v_mul_f32_e32 v230, v230, v238
	v_mul_f32_e32 v231, v231, v239
	v_mul_f32_e32 v118, v118, v224
	v_mul_f32_e32 v119, v119, v225
	v_mul_f32_e32 v120, v120, v226
	v_mul_f32_e32 v121, v121, v227
	v_mul_f32_e32 v114, v114, v228
	v_mul_f32_e32 v115, v115, v229
	v_mul_f32_e32 v116, v116, v230
	v_mul_f32_e32 v117, v117, v231
	v_cvt_pk_bf16_f32 v170, v118, v119
	v_cvt_pk_bf16_f32 v171, v120, v121
	v_cvt_pk_bf16_f32 v172, v114, v115
	v_cvt_pk_bf16_f32 v173, v116, v117
	s_nop 1
	global_store_dwordx4 v134, v[170:173], s[8:9]
	v_mul_f32_e32 v224, 0xbfb8aa3b, v110
	v_mul_f32_e32 v225, 0xbfb8aa3b, v111
	v_mul_f32_e32 v226, 0xbfb8aa3b, v112
	v_mul_f32_e32 v227, 0xbfb8aa3b, v113
	v_mul_f32_e32 v228, 0xbfb8aa3b, v106
	v_mul_f32_e32 v229, 0xbfb8aa3b, v107
	v_mul_f32_e32 v230, 0xbfb8aa3b, v108
	v_mul_f32_e32 v231, 0xbfb8aa3b, v109
	v_mul_f32_e32 v232, 0xbfb8aa3b, v102
	v_mul_f32_e32 v233, 0xbfb8aa3b, v103
	v_mul_f32_e32 v234, 0xbfb8aa3b, v104
	v_mul_f32_e32 v235, 0xbfb8aa3b, v105
	v_mul_f32_e32 v236, 0xbfb8aa3b, v98
	v_mul_f32_e32 v237, 0xbfb8aa3b, v99
	v_mul_f32_e32 v238, 0xbfb8aa3b, v100
	v_mul_f32_e32 v239, 0xbfb8aa3b, v101
	v_exp_f32_e32 v224, v224
	v_exp_f32_e32 v225, v225
	v_exp_f32_e32 v226, v226
	v_exp_f32_e32 v227, v227
	v_exp_f32_e32 v228, v228
	v_exp_f32_e32 v229, v229
	v_exp_f32_e32 v230, v230
	v_exp_f32_e32 v231, v231
	v_exp_f32_e32 v232, v232
	v_exp_f32_e32 v233, v233
	v_exp_f32_e32 v234, v234
	v_exp_f32_e32 v235, v235
	v_exp_f32_e32 v236, v236
	v_exp_f32_e32 v237, v237
	v_exp_f32_e32 v238, v238
	v_exp_f32_e32 v239, v239
	v_add_f32_e32 v224, 1.0, v224
	v_add_f32_e32 v225, 1.0, v225
	v_add_f32_e32 v226, 1.0, v226
	v_add_f32_e32 v227, 1.0, v227
	v_add_f32_e32 v228, 1.0, v228
	v_add_f32_e32 v229, 1.0, v229
	v_add_f32_e32 v230, 1.0, v230
	v_add_f32_e32 v231, 1.0, v231
	v_add_f32_e32 v232, 1.0, v232
	v_add_f32_e32 v233, 1.0, v233
	v_add_f32_e32 v234, 1.0, v234
	v_add_f32_e32 v235, 1.0, v235
	v_add_f32_e32 v236, 1.0, v236
	v_add_f32_e32 v237, 1.0, v237
	v_add_f32_e32 v238, 1.0, v238
	v_add_f32_e32 v239, 1.0, v239
	v_rcp_f32_e32 v224, v224
	v_rcp_f32_e32 v225, v225
	v_rcp_f32_e32 v226, v226
	v_rcp_f32_e32 v227, v227
	v_rcp_f32_e32 v228, v228
	v_rcp_f32_e32 v229, v229
	v_rcp_f32_e32 v230, v230
	v_rcp_f32_e32 v231, v231
	v_rcp_f32_e32 v232, v232
	v_rcp_f32_e32 v233, v233
	v_rcp_f32_e32 v234, v234
	v_rcp_f32_e32 v235, v235
	v_rcp_f32_e32 v236, v236
	v_rcp_f32_e32 v237, v237
	v_rcp_f32_e32 v238, v238
	v_rcp_f32_e32 v239, v239
	v_mul_f32_e32 v102, v102, v232
	v_mul_f32_e32 v103, v103, v233
	v_mul_f32_e32 v104, v104, v234
	v_mul_f32_e32 v105, v105, v235
	v_mul_f32_e32 v98, v98, v236
	v_mul_f32_e32 v99, v99, v237
	v_mul_f32_e32 v100, v100, v238
	v_mul_f32_e32 v101, v101, v239
	s_waitcnt vmcnt(7)
	v_lshlrev_b32_e32 v232, 16, v174
	v_and_b32_e32 v233, 0xffff0000, v174
	v_lshlrev_b32_e32 v234, 16, v175
	v_and_b32_e32 v235, 0xffff0000, v175
	v_lshlrev_b32_e32 v236, 16, v176
	v_and_b32_e32 v237, 0xffff0000, v176
	v_lshlrev_b32_e32 v238, 16, v177
	v_and_b32_e32 v239, 0xffff0000, v177
	v_mul_f32_e32 v224, v224, v232
	v_mul_f32_e32 v225, v225, v233
	v_mul_f32_e32 v226, v226, v234
	v_mul_f32_e32 v227, v227, v235
	v_mul_f32_e32 v228, v228, v236
	v_mul_f32_e32 v229, v229, v237
	v_mul_f32_e32 v230, v230, v238
	v_mul_f32_e32 v231, v231, v239
	v_mul_f32_e32 v102, v102, v224
	v_mul_f32_e32 v103, v103, v225
	v_mul_f32_e32 v104, v104, v226
	v_mul_f32_e32 v105, v105, v227
	v_mul_f32_e32 v98, v98, v228
	v_mul_f32_e32 v99, v99, v229
	v_mul_f32_e32 v100, v100, v230
	v_mul_f32_e32 v101, v101, v231
	v_cvt_pk_bf16_f32 v174, v102, v103
	v_cvt_pk_bf16_f32 v175, v104, v105
	v_cvt_pk_bf16_f32 v176, v98, v99
	v_cvt_pk_bf16_f32 v177, v100, v101
	s_nop 1
	global_store_dwordx4 v135, v[174:177], s[8:9]
	v_mul_f32_e32 v224, 0xbfb8aa3b, v94
	v_mul_f32_e32 v225, 0xbfb8aa3b, v95
	v_mul_f32_e32 v226, 0xbfb8aa3b, v96
	v_mul_f32_e32 v227, 0xbfb8aa3b, v97
	v_mul_f32_e32 v228, 0xbfb8aa3b, v90
	v_mul_f32_e32 v229, 0xbfb8aa3b, v91
	v_mul_f32_e32 v230, 0xbfb8aa3b, v92
	v_mul_f32_e32 v231, 0xbfb8aa3b, v93
	v_mul_f32_e32 v232, 0xbfb8aa3b, v86
	v_mul_f32_e32 v233, 0xbfb8aa3b, v87
	v_mul_f32_e32 v234, 0xbfb8aa3b, v88
	v_mul_f32_e32 v235, 0xbfb8aa3b, v89
	v_mul_f32_e32 v236, 0xbfb8aa3b, v82
	v_mul_f32_e32 v237, 0xbfb8aa3b, v83
	v_mul_f32_e32 v238, 0xbfb8aa3b, v84
	v_mul_f32_e32 v239, 0xbfb8aa3b, v85
	v_exp_f32_e32 v224, v224
	v_exp_f32_e32 v225, v225
	v_exp_f32_e32 v226, v226
	v_exp_f32_e32 v227, v227
	v_exp_f32_e32 v228, v228
	v_exp_f32_e32 v229, v229
	v_exp_f32_e32 v230, v230
	v_exp_f32_e32 v231, v231
	v_exp_f32_e32 v232, v232
	v_exp_f32_e32 v233, v233
	v_exp_f32_e32 v234, v234
	v_exp_f32_e32 v235, v235
	v_exp_f32_e32 v236, v236
	v_exp_f32_e32 v237, v237
	v_exp_f32_e32 v238, v238
	v_exp_f32_e32 v239, v239
	v_add_f32_e32 v224, 1.0, v224
	v_add_f32_e32 v225, 1.0, v225
	v_add_f32_e32 v226, 1.0, v226
	v_add_f32_e32 v227, 1.0, v227
	v_add_f32_e32 v228, 1.0, v228
	v_add_f32_e32 v229, 1.0, v229
	v_add_f32_e32 v230, 1.0, v230
	v_add_f32_e32 v231, 1.0, v231
	v_add_f32_e32 v232, 1.0, v232
	v_add_f32_e32 v233, 1.0, v233
	v_add_f32_e32 v234, 1.0, v234
	v_add_f32_e32 v235, 1.0, v235
	v_add_f32_e32 v236, 1.0, v236
	v_add_f32_e32 v237, 1.0, v237
	v_add_f32_e32 v238, 1.0, v238
	v_add_f32_e32 v239, 1.0, v239
	v_rcp_f32_e32 v224, v224
	v_rcp_f32_e32 v225, v225
	v_rcp_f32_e32 v226, v226
	v_rcp_f32_e32 v227, v227
	v_rcp_f32_e32 v228, v228
	v_rcp_f32_e32 v229, v229
	v_rcp_f32_e32 v230, v230
	v_rcp_f32_e32 v231, v231
	v_rcp_f32_e32 v232, v232
	v_rcp_f32_e32 v233, v233
	v_rcp_f32_e32 v234, v234
	v_rcp_f32_e32 v235, v235
	v_rcp_f32_e32 v236, v236
	v_rcp_f32_e32 v237, v237
	v_rcp_f32_e32 v238, v238
	v_rcp_f32_e32 v239, v239
	v_mul_f32_e32 v86, v86, v232
	v_mul_f32_e32 v87, v87, v233
	v_mul_f32_e32 v88, v88, v234
	v_mul_f32_e32 v89, v89, v235
	v_mul_f32_e32 v82, v82, v236
	v_mul_f32_e32 v83, v83, v237
	v_mul_f32_e32 v84, v84, v238
	v_mul_f32_e32 v85, v85, v239
	s_waitcnt vmcnt(7)
	v_lshlrev_b32_e32 v232, 16, v178
	v_and_b32_e32 v233, 0xffff0000, v178
	v_lshlrev_b32_e32 v234, 16, v179
	v_and_b32_e32 v235, 0xffff0000, v179
	v_lshlrev_b32_e32 v236, 16, v180
	v_and_b32_e32 v237, 0xffff0000, v180
	v_lshlrev_b32_e32 v238, 16, v181
	v_and_b32_e32 v239, 0xffff0000, v181
	v_mul_f32_e32 v224, v224, v232
	v_mul_f32_e32 v225, v225, v233
	v_mul_f32_e32 v226, v226, v234
	v_mul_f32_e32 v227, v227, v235
	v_mul_f32_e32 v228, v228, v236
	v_mul_f32_e32 v229, v229, v237
	v_mul_f32_e32 v230, v230, v238
	v_mul_f32_e32 v231, v231, v239
	v_mul_f32_e32 v86, v86, v224
	v_mul_f32_e32 v87, v87, v225
	v_mul_f32_e32 v88, v88, v226
	v_mul_f32_e32 v89, v89, v227
	v_mul_f32_e32 v82, v82, v228
	v_mul_f32_e32 v83, v83, v229
	v_mul_f32_e32 v84, v84, v230
	v_mul_f32_e32 v85, v85, v231
	v_cvt_pk_bf16_f32 v178, v86, v87
	v_cvt_pk_bf16_f32 v179, v88, v89
	v_cvt_pk_bf16_f32 v180, v82, v83
	v_cvt_pk_bf16_f32 v181, v84, v85
	s_nop 1
	global_store_dwordx4 v136, v[178:181], s[8:9]
	v_mul_f32_e32 v224, 0xbfb8aa3b, v78
	v_mul_f32_e32 v225, 0xbfb8aa3b, v79
	v_mul_f32_e32 v226, 0xbfb8aa3b, v80
	v_mul_f32_e32 v227, 0xbfb8aa3b, v81
	v_mul_f32_e32 v228, 0xbfb8aa3b, v74
	v_mul_f32_e32 v229, 0xbfb8aa3b, v75
	v_mul_f32_e32 v230, 0xbfb8aa3b, v76
	v_mul_f32_e32 v231, 0xbfb8aa3b, v77
	v_mul_f32_e32 v232, 0xbfb8aa3b, v70
	v_mul_f32_e32 v233, 0xbfb8aa3b, v71
	v_mul_f32_e32 v234, 0xbfb8aa3b, v72
	v_mul_f32_e32 v235, 0xbfb8aa3b, v73
	v_mul_f32_e32 v236, 0xbfb8aa3b, v66
	v_mul_f32_e32 v237, 0xbfb8aa3b, v67
	v_mul_f32_e32 v238, 0xbfb8aa3b, v68
	v_mul_f32_e32 v239, 0xbfb8aa3b, v69
	v_exp_f32_e32 v224, v224
	v_exp_f32_e32 v225, v225
	v_exp_f32_e32 v226, v226
	v_exp_f32_e32 v227, v227
	v_exp_f32_e32 v228, v228
	v_exp_f32_e32 v229, v229
	v_exp_f32_e32 v230, v230
	v_exp_f32_e32 v231, v231
	v_exp_f32_e32 v232, v232
	v_exp_f32_e32 v233, v233
	v_exp_f32_e32 v234, v234
	v_exp_f32_e32 v235, v235
	v_exp_f32_e32 v236, v236
	v_exp_f32_e32 v237, v237
	v_exp_f32_e32 v238, v238
	v_exp_f32_e32 v239, v239
	v_add_f32_e32 v224, 1.0, v224
	v_add_f32_e32 v225, 1.0, v225
	v_add_f32_e32 v226, 1.0, v226
	v_add_f32_e32 v227, 1.0, v227
	v_add_f32_e32 v228, 1.0, v228
	v_add_f32_e32 v229, 1.0, v229
	v_add_f32_e32 v230, 1.0, v230
	v_add_f32_e32 v231, 1.0, v231
	v_add_f32_e32 v232, 1.0, v232
	v_add_f32_e32 v233, 1.0, v233
	v_add_f32_e32 v234, 1.0, v234
	v_add_f32_e32 v235, 1.0, v235
	v_add_f32_e32 v236, 1.0, v236
	v_add_f32_e32 v237, 1.0, v237
	v_add_f32_e32 v238, 1.0, v238
	v_add_f32_e32 v239, 1.0, v239
	v_rcp_f32_e32 v224, v224
	v_rcp_f32_e32 v225, v225
	v_rcp_f32_e32 v226, v226
	v_rcp_f32_e32 v227, v227
	v_rcp_f32_e32 v228, v228
	v_rcp_f32_e32 v229, v229
	v_rcp_f32_e32 v230, v230
	v_rcp_f32_e32 v231, v231
	v_rcp_f32_e32 v232, v232
	v_rcp_f32_e32 v233, v233
	v_rcp_f32_e32 v234, v234
	v_rcp_f32_e32 v235, v235
	v_rcp_f32_e32 v236, v236
	v_rcp_f32_e32 v237, v237
	v_rcp_f32_e32 v238, v238
	v_rcp_f32_e32 v239, v239
	v_mul_f32_e32 v70, v70, v232
	v_mul_f32_e32 v71, v71, v233
	v_mul_f32_e32 v72, v72, v234
	v_mul_f32_e32 v73, v73, v235
	v_mul_f32_e32 v66, v66, v236
	v_mul_f32_e32 v67, v67, v237
	v_mul_f32_e32 v68, v68, v238
	v_mul_f32_e32 v69, v69, v239
	s_waitcnt vmcnt(7)
	v_lshlrev_b32_e32 v232, 16, v182
	v_and_b32_e32 v233, 0xffff0000, v182
	v_lshlrev_b32_e32 v234, 16, v183
	v_and_b32_e32 v235, 0xffff0000, v183
	v_lshlrev_b32_e32 v236, 16, v184
	v_and_b32_e32 v237, 0xffff0000, v184
	v_lshlrev_b32_e32 v238, 16, v185
	v_and_b32_e32 v239, 0xffff0000, v185
	v_mul_f32_e32 v224, v224, v232
	v_mul_f32_e32 v225, v225, v233
	v_mul_f32_e32 v226, v226, v234
	v_mul_f32_e32 v227, v227, v235
	v_mul_f32_e32 v228, v228, v236
	v_mul_f32_e32 v229, v229, v237
	v_mul_f32_e32 v230, v230, v238
	v_mul_f32_e32 v231, v231, v239
	v_mul_f32_e32 v70, v70, v224
	v_mul_f32_e32 v71, v71, v225
	v_mul_f32_e32 v72, v72, v226
	v_mul_f32_e32 v73, v73, v227
	v_mul_f32_e32 v66, v66, v228
	v_mul_f32_e32 v67, v67, v229
	v_mul_f32_e32 v68, v68, v230
	v_mul_f32_e32 v69, v69, v231
	v_cvt_pk_bf16_f32 v182, v70, v71
	v_cvt_pk_bf16_f32 v183, v72, v73
	v_cvt_pk_bf16_f32 v184, v66, v67
	v_cvt_pk_bf16_f32 v185, v68, v69
	s_nop 1
	global_store_dwordx4 v137, v[182:185], s[8:9]
	v_mul_f32_e32 v224, 0xbfb8aa3b, v62
	v_mul_f32_e32 v225, 0xbfb8aa3b, v63
	v_mul_f32_e32 v226, 0xbfb8aa3b, v64
	v_mul_f32_e32 v227, 0xbfb8aa3b, v65
	v_mul_f32_e32 v228, 0xbfb8aa3b, v58
	v_mul_f32_e32 v229, 0xbfb8aa3b, v59
	v_mul_f32_e32 v230, 0xbfb8aa3b, v60
	v_mul_f32_e32 v231, 0xbfb8aa3b, v61
	v_mul_f32_e32 v232, 0xbfb8aa3b, v54
	v_mul_f32_e32 v233, 0xbfb8aa3b, v55
	v_mul_f32_e32 v234, 0xbfb8aa3b, v56
	v_mul_f32_e32 v235, 0xbfb8aa3b, v57
	v_mul_f32_e32 v236, 0xbfb8aa3b, v50
	v_mul_f32_e32 v237, 0xbfb8aa3b, v51
	v_mul_f32_e32 v238, 0xbfb8aa3b, v52
	v_mul_f32_e32 v239, 0xbfb8aa3b, v53
	v_exp_f32_e32 v224, v224
	v_exp_f32_e32 v225, v225
	v_exp_f32_e32 v226, v226
	v_exp_f32_e32 v227, v227
	v_exp_f32_e32 v228, v228
	v_exp_f32_e32 v229, v229
	v_exp_f32_e32 v230, v230
	v_exp_f32_e32 v231, v231
	v_exp_f32_e32 v232, v232
	v_exp_f32_e32 v233, v233
	v_exp_f32_e32 v234, v234
	v_exp_f32_e32 v235, v235
	v_exp_f32_e32 v236, v236
	v_exp_f32_e32 v237, v237
	v_exp_f32_e32 v238, v238
	v_exp_f32_e32 v239, v239
	v_add_f32_e32 v224, 1.0, v224
	v_add_f32_e32 v225, 1.0, v225
	v_add_f32_e32 v226, 1.0, v226
	v_add_f32_e32 v227, 1.0, v227
	v_add_f32_e32 v228, 1.0, v228
	v_add_f32_e32 v229, 1.0, v229
	v_add_f32_e32 v230, 1.0, v230
	v_add_f32_e32 v231, 1.0, v231
	v_add_f32_e32 v232, 1.0, v232
	v_add_f32_e32 v233, 1.0, v233
	v_add_f32_e32 v234, 1.0, v234
	v_add_f32_e32 v235, 1.0, v235
	v_add_f32_e32 v236, 1.0, v236
	v_add_f32_e32 v237, 1.0, v237
	v_add_f32_e32 v238, 1.0, v238
	v_add_f32_e32 v239, 1.0, v239
	v_rcp_f32_e32 v224, v224
	v_rcp_f32_e32 v225, v225
	v_rcp_f32_e32 v226, v226
	v_rcp_f32_e32 v227, v227
	v_rcp_f32_e32 v228, v228
	v_rcp_f32_e32 v229, v229
	v_rcp_f32_e32 v230, v230
	v_rcp_f32_e32 v231, v231
	v_rcp_f32_e32 v232, v232
	v_rcp_f32_e32 v233, v233
	v_rcp_f32_e32 v234, v234
	v_rcp_f32_e32 v235, v235
	v_rcp_f32_e32 v236, v236
	v_rcp_f32_e32 v237, v237
	v_rcp_f32_e32 v238, v238
	v_rcp_f32_e32 v239, v239
	v_mul_f32_e32 v54, v54, v232
	v_mul_f32_e32 v55, v55, v233
	v_mul_f32_e32 v56, v56, v234
	v_mul_f32_e32 v57, v57, v235
	v_mul_f32_e32 v50, v50, v236
	v_mul_f32_e32 v51, v51, v237
	v_mul_f32_e32 v52, v52, v238
	v_mul_f32_e32 v53, v53, v239
	s_waitcnt vmcnt(7)
	v_lshlrev_b32_e32 v232, 16, v186
	v_and_b32_e32 v233, 0xffff0000, v186
	v_lshlrev_b32_e32 v234, 16, v187
	v_and_b32_e32 v235, 0xffff0000, v187
	v_lshlrev_b32_e32 v236, 16, v188
	v_and_b32_e32 v237, 0xffff0000, v188
	v_lshlrev_b32_e32 v238, 16, v189
	v_and_b32_e32 v239, 0xffff0000, v189
	v_mul_f32_e32 v224, v224, v232
	v_mul_f32_e32 v225, v225, v233
	v_mul_f32_e32 v226, v226, v234
	v_mul_f32_e32 v227, v227, v235
	v_mul_f32_e32 v228, v228, v236
	v_mul_f32_e32 v229, v229, v237
	v_mul_f32_e32 v230, v230, v238
	v_mul_f32_e32 v231, v231, v239
	v_mul_f32_e32 v54, v54, v224
	v_mul_f32_e32 v55, v55, v225
	v_mul_f32_e32 v56, v56, v226
	v_mul_f32_e32 v57, v57, v227
	v_mul_f32_e32 v50, v50, v228
	v_mul_f32_e32 v51, v51, v229
	v_mul_f32_e32 v52, v52, v230
	v_mul_f32_e32 v53, v53, v231
	v_cvt_pk_bf16_f32 v186, v54, v55
	v_cvt_pk_bf16_f32 v187, v56, v57
	v_cvt_pk_bf16_f32 v188, v50, v51
	v_cvt_pk_bf16_f32 v189, v52, v53
	s_nop 1
	global_store_dwordx4 v158, v[186:189], s[8:9]
	v_mul_f32_e32 v224, 0xbfb8aa3b, v46
	v_mul_f32_e32 v225, 0xbfb8aa3b, v47
	v_mul_f32_e32 v226, 0xbfb8aa3b, v48
	v_mul_f32_e32 v227, 0xbfb8aa3b, v49
	v_mul_f32_e32 v228, 0xbfb8aa3b, v42
	v_mul_f32_e32 v229, 0xbfb8aa3b, v43
	v_mul_f32_e32 v230, 0xbfb8aa3b, v44
	v_mul_f32_e32 v231, 0xbfb8aa3b, v45
	v_mul_f32_e32 v232, 0xbfb8aa3b, v38
	v_mul_f32_e32 v233, 0xbfb8aa3b, v39
	v_mul_f32_e32 v234, 0xbfb8aa3b, v40
	v_mul_f32_e32 v235, 0xbfb8aa3b, v41
	v_mul_f32_e32 v236, 0xbfb8aa3b, v34
	v_mul_f32_e32 v237, 0xbfb8aa3b, v35
	v_mul_f32_e32 v238, 0xbfb8aa3b, v36
	v_mul_f32_e32 v239, 0xbfb8aa3b, v37
	v_exp_f32_e32 v224, v224
	v_exp_f32_e32 v225, v225
	v_exp_f32_e32 v226, v226
	v_exp_f32_e32 v227, v227
	v_exp_f32_e32 v228, v228
	v_exp_f32_e32 v229, v229
	v_exp_f32_e32 v230, v230
	v_exp_f32_e32 v231, v231
	v_exp_f32_e32 v232, v232
	v_exp_f32_e32 v233, v233
	v_exp_f32_e32 v234, v234
	v_exp_f32_e32 v235, v235
	v_exp_f32_e32 v236, v236
	v_exp_f32_e32 v237, v237
	v_exp_f32_e32 v238, v238
	v_exp_f32_e32 v239, v239
	v_add_f32_e32 v224, 1.0, v224
	v_add_f32_e32 v225, 1.0, v225
	v_add_f32_e32 v226, 1.0, v226
	v_add_f32_e32 v227, 1.0, v227
	v_add_f32_e32 v228, 1.0, v228
	v_add_f32_e32 v229, 1.0, v229
	v_add_f32_e32 v230, 1.0, v230
	v_add_f32_e32 v231, 1.0, v231
	v_add_f32_e32 v232, 1.0, v232
	v_add_f32_e32 v233, 1.0, v233
	v_add_f32_e32 v234, 1.0, v234
	v_add_f32_e32 v235, 1.0, v235
	v_add_f32_e32 v236, 1.0, v236
	v_add_f32_e32 v237, 1.0, v237
	v_add_f32_e32 v238, 1.0, v238
	v_add_f32_e32 v239, 1.0, v239
	v_rcp_f32_e32 v224, v224
	v_rcp_f32_e32 v225, v225
	v_rcp_f32_e32 v226, v226
	v_rcp_f32_e32 v227, v227
	v_rcp_f32_e32 v228, v228
	v_rcp_f32_e32 v229, v229
	v_rcp_f32_e32 v230, v230
	v_rcp_f32_e32 v231, v231
	v_rcp_f32_e32 v232, v232
	v_rcp_f32_e32 v233, v233
	v_rcp_f32_e32 v234, v234
	v_rcp_f32_e32 v235, v235
	v_rcp_f32_e32 v236, v236
	v_rcp_f32_e32 v237, v237
	v_rcp_f32_e32 v238, v238
	v_rcp_f32_e32 v239, v239
	v_mul_f32_e32 v38, v38, v232
	v_mul_f32_e32 v39, v39, v233
	v_mul_f32_e32 v40, v40, v234
	v_mul_f32_e32 v41, v41, v235
	v_mul_f32_e32 v34, v34, v236
	v_mul_f32_e32 v35, v35, v237
	v_mul_f32_e32 v36, v36, v238
	v_mul_f32_e32 v37, v37, v239
	s_waitcnt vmcnt(7)
	v_lshlrev_b32_e32 v232, 16, v190
	v_and_b32_e32 v233, 0xffff0000, v190
	v_lshlrev_b32_e32 v234, 16, v191
	v_and_b32_e32 v235, 0xffff0000, v191
	v_lshlrev_b32_e32 v236, 16, v192
	v_and_b32_e32 v237, 0xffff0000, v192
	v_lshlrev_b32_e32 v238, 16, v193
	v_and_b32_e32 v239, 0xffff0000, v193
	v_mul_f32_e32 v224, v224, v232
	v_mul_f32_e32 v225, v225, v233
	v_mul_f32_e32 v226, v226, v234
	v_mul_f32_e32 v227, v227, v235
	v_mul_f32_e32 v228, v228, v236
	v_mul_f32_e32 v229, v229, v237
	v_mul_f32_e32 v230, v230, v238
	v_mul_f32_e32 v231, v231, v239
	v_mul_f32_e32 v38, v38, v224
	v_mul_f32_e32 v39, v39, v225
	v_mul_f32_e32 v40, v40, v226
	v_mul_f32_e32 v41, v41, v227
	v_mul_f32_e32 v34, v34, v228
	v_mul_f32_e32 v35, v35, v229
	v_mul_f32_e32 v36, v36, v230
	v_mul_f32_e32 v37, v37, v231
	v_cvt_pk_bf16_f32 v190, v38, v39
	v_cvt_pk_bf16_f32 v191, v40, v41
	v_cvt_pk_bf16_f32 v192, v34, v35
	v_cvt_pk_bf16_f32 v193, v36, v37
	s_nop 1
	global_store_dwordx4 v159, v[190:193], s[8:9]
	v_mul_f32_e32 v224, 0xbfb8aa3b, v30
	v_mul_f32_e32 v225, 0xbfb8aa3b, v31
	v_mul_f32_e32 v226, 0xbfb8aa3b, v32
	v_mul_f32_e32 v227, 0xbfb8aa3b, v33
	v_mul_f32_e32 v228, 0xbfb8aa3b, v26
	v_mul_f32_e32 v229, 0xbfb8aa3b, v27
	v_mul_f32_e32 v230, 0xbfb8aa3b, v28
	v_mul_f32_e32 v231, 0xbfb8aa3b, v29
	v_mul_f32_e32 v232, 0xbfb8aa3b, v22
	v_mul_f32_e32 v233, 0xbfb8aa3b, v23
	v_mul_f32_e32 v234, 0xbfb8aa3b, v24
	v_mul_f32_e32 v235, 0xbfb8aa3b, v25
	v_mul_f32_e32 v236, 0xbfb8aa3b, v18
	v_mul_f32_e32 v237, 0xbfb8aa3b, v19
	v_mul_f32_e32 v238, 0xbfb8aa3b, v20
	v_mul_f32_e32 v239, 0xbfb8aa3b, v21
	v_exp_f32_e32 v224, v224
	v_exp_f32_e32 v225, v225
	v_exp_f32_e32 v226, v226
	v_exp_f32_e32 v227, v227
	v_exp_f32_e32 v228, v228
	v_exp_f32_e32 v229, v229
	v_exp_f32_e32 v230, v230
	v_exp_f32_e32 v231, v231
	v_exp_f32_e32 v232, v232
	v_exp_f32_e32 v233, v233
	v_exp_f32_e32 v234, v234
	v_exp_f32_e32 v235, v235
	v_exp_f32_e32 v236, v236
	v_exp_f32_e32 v237, v237
	v_exp_f32_e32 v238, v238
	v_exp_f32_e32 v239, v239
	v_add_f32_e32 v224, 1.0, v224
	v_add_f32_e32 v225, 1.0, v225
	v_add_f32_e32 v226, 1.0, v226
	v_add_f32_e32 v227, 1.0, v227
	v_add_f32_e32 v228, 1.0, v228
	v_add_f32_e32 v229, 1.0, v229
	v_add_f32_e32 v230, 1.0, v230
	v_add_f32_e32 v231, 1.0, v231
	v_add_f32_e32 v232, 1.0, v232
	v_add_f32_e32 v233, 1.0, v233
	v_add_f32_e32 v234, 1.0, v234
	v_add_f32_e32 v235, 1.0, v235
	v_add_f32_e32 v236, 1.0, v236
	v_add_f32_e32 v237, 1.0, v237
	v_add_f32_e32 v238, 1.0, v238
	v_add_f32_e32 v239, 1.0, v239
	v_rcp_f32_e32 v224, v224
	v_rcp_f32_e32 v225, v225
	v_rcp_f32_e32 v226, v226
	v_rcp_f32_e32 v227, v227
	v_rcp_f32_e32 v228, v228
	v_rcp_f32_e32 v229, v229
	v_rcp_f32_e32 v230, v230
	v_rcp_f32_e32 v231, v231
	v_rcp_f32_e32 v232, v232
	v_rcp_f32_e32 v233, v233
	v_rcp_f32_e32 v234, v234
	v_rcp_f32_e32 v235, v235
	v_rcp_f32_e32 v236, v236
	v_rcp_f32_e32 v237, v237
	v_rcp_f32_e32 v238, v238
	v_rcp_f32_e32 v239, v239
	v_mul_f32_e32 v22, v22, v232
	v_mul_f32_e32 v23, v23, v233
	v_mul_f32_e32 v24, v24, v234
	v_mul_f32_e32 v25, v25, v235
	v_mul_f32_e32 v18, v18, v236
	v_mul_f32_e32 v19, v19, v237
	v_mul_f32_e32 v20, v20, v238
	v_mul_f32_e32 v21, v21, v239
	s_waitcnt vmcnt(7)
	v_lshlrev_b32_e32 v232, 16, v194
	v_and_b32_e32 v233, 0xffff0000, v194
	v_lshlrev_b32_e32 v234, 16, v195
	v_and_b32_e32 v235, 0xffff0000, v195
	v_lshlrev_b32_e32 v236, 16, v196
	v_and_b32_e32 v237, 0xffff0000, v196
	v_lshlrev_b32_e32 v238, 16, v197
	v_and_b32_e32 v239, 0xffff0000, v197
	v_mul_f32_e32 v224, v224, v232
	v_mul_f32_e32 v225, v225, v233
	v_mul_f32_e32 v226, v226, v234
	v_mul_f32_e32 v227, v227, v235
	v_mul_f32_e32 v228, v228, v236
	v_mul_f32_e32 v229, v229, v237
	v_mul_f32_e32 v230, v230, v238
	v_mul_f32_e32 v231, v231, v239
	v_mul_f32_e32 v22, v22, v224
	v_mul_f32_e32 v23, v23, v225
	v_mul_f32_e32 v24, v24, v226
	v_mul_f32_e32 v25, v25, v227
	v_mul_f32_e32 v18, v18, v228
	v_mul_f32_e32 v19, v19, v229
	v_mul_f32_e32 v20, v20, v230
	v_mul_f32_e32 v21, v21, v231
	v_cvt_pk_bf16_f32 v194, v22, v23
	v_cvt_pk_bf16_f32 v195, v24, v25
	v_cvt_pk_bf16_f32 v196, v18, v19
	v_cvt_pk_bf16_f32 v197, v20, v21
	s_nop 1
	global_store_dwordx4 v160, v[194:197], s[8:9]
	v_mul_f32_e32 v224, 0xbfb8aa3b, v14
	v_mul_f32_e32 v225, 0xbfb8aa3b, v15
	v_mul_f32_e32 v226, 0xbfb8aa3b, v16
	v_mul_f32_e32 v227, 0xbfb8aa3b, v17
	v_mul_f32_e32 v228, 0xbfb8aa3b, v10
	v_mul_f32_e32 v229, 0xbfb8aa3b, v11
	v_mul_f32_e32 v230, 0xbfb8aa3b, v12
	v_mul_f32_e32 v231, 0xbfb8aa3b, v13
	v_mul_f32_e32 v232, 0xbfb8aa3b, v6
	v_mul_f32_e32 v233, 0xbfb8aa3b, v7
	v_mul_f32_e32 v234, 0xbfb8aa3b, v8
	v_mul_f32_e32 v235, 0xbfb8aa3b, v9
	v_mul_f32_e32 v236, 0xbfb8aa3b, v2
	v_mul_f32_e32 v237, 0xbfb8aa3b, v3
	v_mul_f32_e32 v238, 0xbfb8aa3b, v4
	v_mul_f32_e32 v239, 0xbfb8aa3b, v5
	v_exp_f32_e32 v224, v224
	v_exp_f32_e32 v225, v225
	v_exp_f32_e32 v226, v226
	v_exp_f32_e32 v227, v227
	v_exp_f32_e32 v228, v228
	v_exp_f32_e32 v229, v229
	v_exp_f32_e32 v230, v230
	v_exp_f32_e32 v231, v231
	v_exp_f32_e32 v232, v232
	v_exp_f32_e32 v233, v233
	v_exp_f32_e32 v234, v234
	v_exp_f32_e32 v235, v235
	v_exp_f32_e32 v236, v236
	v_exp_f32_e32 v237, v237
	v_exp_f32_e32 v238, v238
	v_exp_f32_e32 v239, v239
	v_add_f32_e32 v224, 1.0, v224
	v_add_f32_e32 v225, 1.0, v225
	v_add_f32_e32 v226, 1.0, v226
	v_add_f32_e32 v227, 1.0, v227
	v_add_f32_e32 v228, 1.0, v228
	v_add_f32_e32 v229, 1.0, v229
	v_add_f32_e32 v230, 1.0, v230
	v_add_f32_e32 v231, 1.0, v231
	v_add_f32_e32 v232, 1.0, v232
	v_add_f32_e32 v233, 1.0, v233
	v_add_f32_e32 v234, 1.0, v234
	v_add_f32_e32 v235, 1.0, v235
	v_add_f32_e32 v236, 1.0, v236
	v_add_f32_e32 v237, 1.0, v237
	v_add_f32_e32 v238, 1.0, v238
	v_add_f32_e32 v239, 1.0, v239
	v_rcp_f32_e32 v224, v224
	v_rcp_f32_e32 v225, v225
	v_rcp_f32_e32 v226, v226
	v_rcp_f32_e32 v227, v227
	v_rcp_f32_e32 v228, v228
	v_rcp_f32_e32 v229, v229
	v_rcp_f32_e32 v230, v230
	v_rcp_f32_e32 v231, v231
	v_rcp_f32_e32 v232, v232
	v_rcp_f32_e32 v233, v233
	v_rcp_f32_e32 v234, v234
	v_rcp_f32_e32 v235, v235
	v_rcp_f32_e32 v236, v236
	v_rcp_f32_e32 v237, v237
	v_rcp_f32_e32 v238, v238
	v_rcp_f32_e32 v239, v239
	v_mul_f32_e32 v6, v6, v232
	v_mul_f32_e32 v7, v7, v233
	v_mul_f32_e32 v8, v8, v234
	v_mul_f32_e32 v9, v9, v235
	v_mul_f32_e32 v2, v2, v236
	v_mul_f32_e32 v3, v3, v237
	v_mul_f32_e32 v4, v4, v238
	v_mul_f32_e32 v5, v5, v239
	s_waitcnt vmcnt(7)
	v_lshlrev_b32_e32 v232, 16, v198
	v_and_b32_e32 v233, 0xffff0000, v198
	v_lshlrev_b32_e32 v234, 16, v199
	v_and_b32_e32 v235, 0xffff0000, v199
	v_lshlrev_b32_e32 v236, 16, v200
	v_and_b32_e32 v237, 0xffff0000, v200
	v_lshlrev_b32_e32 v238, 16, v201
	v_and_b32_e32 v239, 0xffff0000, v201
	v_mul_f32_e32 v224, v224, v232
	v_mul_f32_e32 v225, v225, v233
	v_mul_f32_e32 v226, v226, v234
	v_mul_f32_e32 v227, v227, v235
	v_mul_f32_e32 v228, v228, v236
	v_mul_f32_e32 v229, v229, v237
	v_mul_f32_e32 v230, v230, v238
	v_mul_f32_e32 v231, v231, v239
	v_mul_f32_e32 v6, v6, v224
	v_mul_f32_e32 v7, v7, v225
	v_mul_f32_e32 v8, v8, v226
	v_mul_f32_e32 v9, v9, v227
	v_mul_f32_e32 v2, v2, v228
	v_mul_f32_e32 v3, v3, v229
	v_mul_f32_e32 v4, v4, v230
	v_mul_f32_e32 v5, v5, v231
	v_cvt_pk_bf16_f32 v198, v6, v7
	v_cvt_pk_bf16_f32 v199, v8, v9
	v_cvt_pk_bf16_f32 v200, v2, v3
	v_cvt_pk_bf16_f32 v201, v4, v5
	s_nop 1
	global_store_dwordx4 v161, v[198:201], s[8:9]
	s_branch .LBB0_1464
.LBB0_1466:
	s_lshl_b32 s13, s20, 8
	s_ashr_i32 s11, s20, 1
	s_and_b32 s13, s13, 0x100
	v_or_b32_e32 v0, s13, v168
	s_mul_hi_i32 s13, s11, 0x1200000
	s_mul_i32 s11, s11, 0x1200000
	s_add_u32 s26, s78, s11
	s_addc_u32 s27, s79, s13
	v_lshlrev_b32_e32 v0, 1, v0
	v_lshl_add_u32 v134, v156, 10, v0
	v_add_u32_e32 v135, 0x4000, v134
	v_add_u32_e32 v136, 0x8000, v134
	v_add_u32_e32 v137, 0xc000, v134
	v_add_u32_e32 v158, 0x20000, v134
	v_add_u32_e32 v159, 0x24000, v134
	v_add_u32_e32 v160, 0x28000, v134
	v_add_u32_e32 v161, 0x2c000, v134
	global_load_dwordx4 v[170:173], v134, s[26:27]
	global_load_dwordx4 v[174:177], v134, s[26:27] offset:256
	global_load_dwordx4 v[178:181], v135, s[26:27]
	global_load_dwordx4 v[182:185], v135, s[26:27] offset:256
	global_load_dwordx4 v[186:189], v136, s[26:27]
	global_load_dwordx4 v[190:193], v136, s[26:27] offset:256
	global_load_dwordx4 v[194:197], v137, s[26:27]
	global_load_dwordx4 v[198:201], v137, s[26:27] offset:256
	global_load_dwordx4 v[202:205], v158, s[26:27]
	global_load_dwordx4 v[206:209], v158, s[26:27] offset:256
	global_load_dwordx4 v[224:227], v159, s[26:27]
	global_load_dwordx4 v[228:231], v159, s[26:27] offset:256
	global_load_dwordx4 v[232:235], v160, s[26:27]
	global_load_dwordx4 v[236:239], v160, s[26:27] offset:256
	global_load_dwordx4 v[240:243], v161, s[26:27]
	global_load_dwordx4 v[244:247], v161, s[26:27] offset:256
	v_mul_f32_e32 v248, 0xbfb8aa3b, v126
	v_mul_f32_e32 v249, 0xbfb8aa3b, v127
	v_mul_f32_e32 v250, 0xbfb8aa3b, v128
	v_mul_f32_e32 v251, 0xbfb8aa3b, v129
	v_mul_f32_e32 v252, 0xbfb8aa3b, v122
	v_mul_f32_e32 v253, 0xbfb8aa3b, v123
	v_mul_f32_e32 v254, 0xbfb8aa3b, v124
	v_mul_f32_e32 v210, 0xbfb8aa3b, v125
	v_exp_f32_e32 v248, v248
	v_exp_f32_e32 v249, v249
	v_exp_f32_e32 v250, v250
	v_exp_f32_e32 v251, v251
	v_exp_f32_e32 v252, v252
	v_exp_f32_e32 v253, v253
	v_exp_f32_e32 v254, v254
	v_exp_f32_e32 v210, v210
	v_add_f32_e32 v248, 1.0, v248
	v_add_f32_e32 v249, 1.0, v249
	v_add_f32_e32 v250, 1.0, v250
	v_add_f32_e32 v251, 1.0, v251
	v_add_f32_e32 v252, 1.0, v252
	v_add_f32_e32 v253, 1.0, v253
	v_add_f32_e32 v254, 1.0, v254
	v_add_f32_e32 v210, 1.0, v210
	v_rcp_f32_e32 v248, v248
	v_rcp_f32_e32 v249, v249
	v_rcp_f32_e32 v250, v250
	v_rcp_f32_e32 v251, v251
	v_rcp_f32_e32 v252, v252
	v_rcp_f32_e32 v253, v253
	v_rcp_f32_e32 v254, v254
	v_rcp_f32_e32 v210, v210
	v_mul_f32_e32 v126, v126, v248
	v_mul_f32_e32 v127, v127, v249
	v_mul_f32_e32 v128, v128, v250
	v_mul_f32_e32 v129, v129, v251
	v_mul_f32_e32 v122, v122, v252
	v_mul_f32_e32 v123, v123, v253
	v_mul_f32_e32 v124, v124, v254
	v_mul_f32_e32 v125, v125, v210
	s_waitcnt vmcnt(15)
	v_lshlrev_b32_e32 v248, 16, v170
	v_and_b32_e32 v249, 0xffff0000, v170
	v_lshlrev_b32_e32 v250, 16, v171
	v_and_b32_e32 v251, 0xffff0000, v171
	v_lshlrev_b32_e32 v252, 16, v172
	v_and_b32_e32 v253, 0xffff0000, v172
	v_lshlrev_b32_e32 v254, 16, v173
	v_and_b32_e32 v210, 0xffff0000, v173
	v_mul_f32_e32 v126, v126, v248
	v_mul_f32_e32 v127, v127, v249
	v_mul_f32_e32 v128, v128, v250
	v_mul_f32_e32 v129, v129, v251
	v_mul_f32_e32 v122, v122, v252
	v_mul_f32_e32 v123, v123, v253
	v_mul_f32_e32 v124, v124, v254
	v_mul_f32_e32 v125, v125, v210
	v_cvt_pk_bf16_f32 v170, v126, v127
	v_cvt_pk_bf16_f32 v171, v128, v129
	v_cvt_pk_bf16_f32 v172, v122, v123
	v_cvt_pk_bf16_f32 v173, v124, v125
	s_nop 1
	global_store_dwordx4 v134, v[170:173], s[26:27]
	v_mul_f32_e32 v248, 0xbfb8aa3b, v118
	v_mul_f32_e32 v249, 0xbfb8aa3b, v119
	v_mul_f32_e32 v250, 0xbfb8aa3b, v120
	v_mul_f32_e32 v251, 0xbfb8aa3b, v121
	v_mul_f32_e32 v252, 0xbfb8aa3b, v114
	v_mul_f32_e32 v253, 0xbfb8aa3b, v115
	v_mul_f32_e32 v254, 0xbfb8aa3b, v116
	v_mul_f32_e32 v210, 0xbfb8aa3b, v117
	v_exp_f32_e32 v248, v248
	v_exp_f32_e32 v249, v249
	v_exp_f32_e32 v250, v250
	v_exp_f32_e32 v251, v251
	v_exp_f32_e32 v252, v252
	v_exp_f32_e32 v253, v253
	v_exp_f32_e32 v254, v254
	v_exp_f32_e32 v210, v210
	v_add_f32_e32 v248, 1.0, v248
	v_add_f32_e32 v249, 1.0, v249
	v_add_f32_e32 v250, 1.0, v250
	v_add_f32_e32 v251, 1.0, v251
	v_add_f32_e32 v252, 1.0, v252
	v_add_f32_e32 v253, 1.0, v253
	v_add_f32_e32 v254, 1.0, v254
	v_add_f32_e32 v210, 1.0, v210
	v_rcp_f32_e32 v248, v248
	v_rcp_f32_e32 v249, v249
	v_rcp_f32_e32 v250, v250
	v_rcp_f32_e32 v251, v251
	v_rcp_f32_e32 v252, v252
	v_rcp_f32_e32 v253, v253
	v_rcp_f32_e32 v254, v254
	v_rcp_f32_e32 v210, v210
	v_mul_f32_e32 v118, v118, v248
	v_mul_f32_e32 v119, v119, v249
	v_mul_f32_e32 v120, v120, v250
	v_mul_f32_e32 v121, v121, v251
	v_mul_f32_e32 v114, v114, v252
	v_mul_f32_e32 v115, v115, v253
	v_mul_f32_e32 v116, v116, v254
	v_mul_f32_e32 v117, v117, v210
	s_waitcnt vmcnt(15)
	v_lshlrev_b32_e32 v248, 16, v174
	v_and_b32_e32 v249, 0xffff0000, v174
	v_lshlrev_b32_e32 v250, 16, v175
	v_and_b32_e32 v251, 0xffff0000, v175
	v_lshlrev_b32_e32 v252, 16, v176
	v_and_b32_e32 v253, 0xffff0000, v176
	v_lshlrev_b32_e32 v254, 16, v177
	v_and_b32_e32 v210, 0xffff0000, v177
	v_mul_f32_e32 v118, v118, v248
	v_mul_f32_e32 v119, v119, v249
	v_mul_f32_e32 v120, v120, v250
	v_mul_f32_e32 v121, v121, v251
	v_mul_f32_e32 v114, v114, v252
	v_mul_f32_e32 v115, v115, v253
	v_mul_f32_e32 v116, v116, v254
	v_mul_f32_e32 v117, v117, v210
	v_cvt_pk_bf16_f32 v174, v118, v119
	v_cvt_pk_bf16_f32 v175, v120, v121
	v_cvt_pk_bf16_f32 v176, v114, v115
	v_cvt_pk_bf16_f32 v177, v116, v117
	s_nop 1
	global_store_dwordx4 v134, v[174:177], s[26:27] offset:256
	v_mul_f32_e32 v248, 0xbfb8aa3b, v110
	v_mul_f32_e32 v249, 0xbfb8aa3b, v111
	v_mul_f32_e32 v250, 0xbfb8aa3b, v112
	v_mul_f32_e32 v251, 0xbfb8aa3b, v113
	v_mul_f32_e32 v252, 0xbfb8aa3b, v106
	v_mul_f32_e32 v253, 0xbfb8aa3b, v107
	v_mul_f32_e32 v254, 0xbfb8aa3b, v108
	v_mul_f32_e32 v210, 0xbfb8aa3b, v109
	v_exp_f32_e32 v248, v248
	v_exp_f32_e32 v249, v249
	v_exp_f32_e32 v250, v250
	v_exp_f32_e32 v251, v251
	v_exp_f32_e32 v252, v252
	v_exp_f32_e32 v253, v253
	v_exp_f32_e32 v254, v254
	v_exp_f32_e32 v210, v210
	v_add_f32_e32 v248, 1.0, v248
	v_add_f32_e32 v249, 1.0, v249
	v_add_f32_e32 v250, 1.0, v250
	v_add_f32_e32 v251, 1.0, v251
	v_add_f32_e32 v252, 1.0, v252
	v_add_f32_e32 v253, 1.0, v253
	v_add_f32_e32 v254, 1.0, v254
	v_add_f32_e32 v210, 1.0, v210
	v_rcp_f32_e32 v248, v248
	v_rcp_f32_e32 v249, v249
	v_rcp_f32_e32 v250, v250
	v_rcp_f32_e32 v251, v251
	v_rcp_f32_e32 v252, v252
	v_rcp_f32_e32 v253, v253
	v_rcp_f32_e32 v254, v254
	v_rcp_f32_e32 v210, v210
	v_mul_f32_e32 v110, v110, v248
	v_mul_f32_e32 v111, v111, v249
	v_mul_f32_e32 v112, v112, v250
	v_mul_f32_e32 v113, v113, v251
	v_mul_f32_e32 v106, v106, v252
	v_mul_f32_e32 v107, v107, v253
	v_mul_f32_e32 v108, v108, v254
	v_mul_f32_e32 v109, v109, v210
	s_waitcnt vmcnt(15)
	v_lshlrev_b32_e32 v248, 16, v178
	v_and_b32_e32 v249, 0xffff0000, v178
	v_lshlrev_b32_e32 v250, 16, v179
	v_and_b32_e32 v251, 0xffff0000, v179
	v_lshlrev_b32_e32 v252, 16, v180
	v_and_b32_e32 v253, 0xffff0000, v180
	v_lshlrev_b32_e32 v254, 16, v181
	v_and_b32_e32 v210, 0xffff0000, v181
	v_mul_f32_e32 v110, v110, v248
	v_mul_f32_e32 v111, v111, v249
	v_mul_f32_e32 v112, v112, v250
	v_mul_f32_e32 v113, v113, v251
	v_mul_f32_e32 v106, v106, v252
	v_mul_f32_e32 v107, v107, v253
	v_mul_f32_e32 v108, v108, v254
	v_mul_f32_e32 v109, v109, v210
	v_cvt_pk_bf16_f32 v178, v110, v111
	v_cvt_pk_bf16_f32 v179, v112, v113
	v_cvt_pk_bf16_f32 v180, v106, v107
	v_cvt_pk_bf16_f32 v181, v108, v109
	s_nop 1
	global_store_dwordx4 v135, v[178:181], s[26:27]
	v_mul_f32_e32 v248, 0xbfb8aa3b, v102
	v_mul_f32_e32 v249, 0xbfb8aa3b, v103
	v_mul_f32_e32 v250, 0xbfb8aa3b, v104
	v_mul_f32_e32 v251, 0xbfb8aa3b, v105
	v_mul_f32_e32 v252, 0xbfb8aa3b, v98
	v_mul_f32_e32 v253, 0xbfb8aa3b, v99
	v_mul_f32_e32 v254, 0xbfb8aa3b, v100
	v_mul_f32_e32 v210, 0xbfb8aa3b, v101
	v_exp_f32_e32 v248, v248
	v_exp_f32_e32 v249, v249
	v_exp_f32_e32 v250, v250
	v_exp_f32_e32 v251, v251
	v_exp_f32_e32 v252, v252
	v_exp_f32_e32 v253, v253
	v_exp_f32_e32 v254, v254
	v_exp_f32_e32 v210, v210
	v_add_f32_e32 v248, 1.0, v248
	v_add_f32_e32 v249, 1.0, v249
	v_add_f32_e32 v250, 1.0, v250
	v_add_f32_e32 v251, 1.0, v251
	v_add_f32_e32 v252, 1.0, v252
	v_add_f32_e32 v253, 1.0, v253
	v_add_f32_e32 v254, 1.0, v254
	v_add_f32_e32 v210, 1.0, v210
	v_rcp_f32_e32 v248, v248
	v_rcp_f32_e32 v249, v249
	v_rcp_f32_e32 v250, v250
	v_rcp_f32_e32 v251, v251
	v_rcp_f32_e32 v252, v252
	v_rcp_f32_e32 v253, v253
	v_rcp_f32_e32 v254, v254
	v_rcp_f32_e32 v210, v210
	v_mul_f32_e32 v102, v102, v248
	v_mul_f32_e32 v103, v103, v249
	v_mul_f32_e32 v104, v104, v250
	v_mul_f32_e32 v105, v105, v251
	v_mul_f32_e32 v98, v98, v252
	v_mul_f32_e32 v99, v99, v253
	v_mul_f32_e32 v100, v100, v254
	v_mul_f32_e32 v101, v101, v210
	s_waitcnt vmcnt(15)
	v_lshlrev_b32_e32 v248, 16, v182
	v_and_b32_e32 v249, 0xffff0000, v182
	v_lshlrev_b32_e32 v250, 16, v183
	v_and_b32_e32 v251, 0xffff0000, v183
	v_lshlrev_b32_e32 v252, 16, v184
	v_and_b32_e32 v253, 0xffff0000, v184
	v_lshlrev_b32_e32 v254, 16, v185
	v_and_b32_e32 v210, 0xffff0000, v185
	v_mul_f32_e32 v102, v102, v248
	v_mul_f32_e32 v103, v103, v249
	v_mul_f32_e32 v104, v104, v250
	v_mul_f32_e32 v105, v105, v251
	v_mul_f32_e32 v98, v98, v252
	v_mul_f32_e32 v99, v99, v253
	v_mul_f32_e32 v100, v100, v254
	v_mul_f32_e32 v101, v101, v210
	v_cvt_pk_bf16_f32 v182, v102, v103
	v_cvt_pk_bf16_f32 v183, v104, v105
	v_cvt_pk_bf16_f32 v184, v98, v99
	v_cvt_pk_bf16_f32 v185, v100, v101
	s_nop 1
	global_store_dwordx4 v135, v[182:185], s[26:27] offset:256
	v_mul_f32_e32 v248, 0xbfb8aa3b, v94
	v_mul_f32_e32 v249, 0xbfb8aa3b, v95
	v_mul_f32_e32 v250, 0xbfb8aa3b, v96
	v_mul_f32_e32 v251, 0xbfb8aa3b, v97
	v_mul_f32_e32 v252, 0xbfb8aa3b, v90
	v_mul_f32_e32 v253, 0xbfb8aa3b, v91
	v_mul_f32_e32 v254, 0xbfb8aa3b, v92
	v_mul_f32_e32 v210, 0xbfb8aa3b, v93
	v_exp_f32_e32 v248, v248
	v_exp_f32_e32 v249, v249
	v_exp_f32_e32 v250, v250
	v_exp_f32_e32 v251, v251
	v_exp_f32_e32 v252, v252
	v_exp_f32_e32 v253, v253
	v_exp_f32_e32 v254, v254
	v_exp_f32_e32 v210, v210
	v_add_f32_e32 v248, 1.0, v248
	v_add_f32_e32 v249, 1.0, v249
	v_add_f32_e32 v250, 1.0, v250
	v_add_f32_e32 v251, 1.0, v251
	v_add_f32_e32 v252, 1.0, v252
	v_add_f32_e32 v253, 1.0, v253
	v_add_f32_e32 v254, 1.0, v254
	v_add_f32_e32 v210, 1.0, v210
	v_rcp_f32_e32 v248, v248
	v_rcp_f32_e32 v249, v249
	v_rcp_f32_e32 v250, v250
	v_rcp_f32_e32 v251, v251
	v_rcp_f32_e32 v252, v252
	v_rcp_f32_e32 v253, v253
	v_rcp_f32_e32 v254, v254
	v_rcp_f32_e32 v210, v210
	v_mul_f32_e32 v94, v94, v248
	v_mul_f32_e32 v95, v95, v249
	v_mul_f32_e32 v96, v96, v250
	v_mul_f32_e32 v97, v97, v251
	v_mul_f32_e32 v90, v90, v252
	v_mul_f32_e32 v91, v91, v253
	v_mul_f32_e32 v92, v92, v254
	v_mul_f32_e32 v93, v93, v210
	s_waitcnt vmcnt(15)
	v_lshlrev_b32_e32 v248, 16, v186
	v_and_b32_e32 v249, 0xffff0000, v186
	v_lshlrev_b32_e32 v250, 16, v187
	v_and_b32_e32 v251, 0xffff0000, v187
	v_lshlrev_b32_e32 v252, 16, v188
	v_and_b32_e32 v253, 0xffff0000, v188
	v_lshlrev_b32_e32 v254, 16, v189
	v_and_b32_e32 v210, 0xffff0000, v189
	v_mul_f32_e32 v94, v94, v248
	v_mul_f32_e32 v95, v95, v249
	v_mul_f32_e32 v96, v96, v250
	v_mul_f32_e32 v97, v97, v251
	v_mul_f32_e32 v90, v90, v252
	v_mul_f32_e32 v91, v91, v253
	v_mul_f32_e32 v92, v92, v254
	v_mul_f32_e32 v93, v93, v210
	v_cvt_pk_bf16_f32 v186, v94, v95
	v_cvt_pk_bf16_f32 v187, v96, v97
	v_cvt_pk_bf16_f32 v188, v90, v91
	v_cvt_pk_bf16_f32 v189, v92, v93
	s_nop 1
	global_store_dwordx4 v136, v[186:189], s[26:27]
	v_mul_f32_e32 v248, 0xbfb8aa3b, v86
	v_mul_f32_e32 v249, 0xbfb8aa3b, v87
	v_mul_f32_e32 v250, 0xbfb8aa3b, v88
	v_mul_f32_e32 v251, 0xbfb8aa3b, v89
	v_mul_f32_e32 v252, 0xbfb8aa3b, v82
	v_mul_f32_e32 v253, 0xbfb8aa3b, v83
	v_mul_f32_e32 v254, 0xbfb8aa3b, v84
	v_mul_f32_e32 v210, 0xbfb8aa3b, v85
	v_exp_f32_e32 v248, v248
	v_exp_f32_e32 v249, v249
	v_exp_f32_e32 v250, v250
	v_exp_f32_e32 v251, v251
	v_exp_f32_e32 v252, v252
	v_exp_f32_e32 v253, v253
	v_exp_f32_e32 v254, v254
	v_exp_f32_e32 v210, v210
	v_add_f32_e32 v248, 1.0, v248
	v_add_f32_e32 v249, 1.0, v249
	v_add_f32_e32 v250, 1.0, v250
	v_add_f32_e32 v251, 1.0, v251
	v_add_f32_e32 v252, 1.0, v252
	v_add_f32_e32 v253, 1.0, v253
	v_add_f32_e32 v254, 1.0, v254
	v_add_f32_e32 v210, 1.0, v210
	v_rcp_f32_e32 v248, v248
	v_rcp_f32_e32 v249, v249
	v_rcp_f32_e32 v250, v250
	v_rcp_f32_e32 v251, v251
	v_rcp_f32_e32 v252, v252
	v_rcp_f32_e32 v253, v253
	v_rcp_f32_e32 v254, v254
	v_rcp_f32_e32 v210, v210
	v_mul_f32_e32 v86, v86, v248
	v_mul_f32_e32 v87, v87, v249
	v_mul_f32_e32 v88, v88, v250
	v_mul_f32_e32 v89, v89, v251
	v_mul_f32_e32 v82, v82, v252
	v_mul_f32_e32 v83, v83, v253
	v_mul_f32_e32 v84, v84, v254
	v_mul_f32_e32 v85, v85, v210
	s_waitcnt vmcnt(15)
	v_lshlrev_b32_e32 v248, 16, v190
	v_and_b32_e32 v249, 0xffff0000, v190
	v_lshlrev_b32_e32 v250, 16, v191
	v_and_b32_e32 v251, 0xffff0000, v191
	v_lshlrev_b32_e32 v252, 16, v192
	v_and_b32_e32 v253, 0xffff0000, v192
	v_lshlrev_b32_e32 v254, 16, v193
	v_and_b32_e32 v210, 0xffff0000, v193
	v_mul_f32_e32 v86, v86, v248
	v_mul_f32_e32 v87, v87, v249
	v_mul_f32_e32 v88, v88, v250
	v_mul_f32_e32 v89, v89, v251
	v_mul_f32_e32 v82, v82, v252
	v_mul_f32_e32 v83, v83, v253
	v_mul_f32_e32 v84, v84, v254
	v_mul_f32_e32 v85, v85, v210
	v_cvt_pk_bf16_f32 v190, v86, v87
	v_cvt_pk_bf16_f32 v191, v88, v89
	v_cvt_pk_bf16_f32 v192, v82, v83
	v_cvt_pk_bf16_f32 v193, v84, v85
	s_nop 1
	global_store_dwordx4 v136, v[190:193], s[26:27] offset:256
	v_mul_f32_e32 v248, 0xbfb8aa3b, v78
	v_mul_f32_e32 v249, 0xbfb8aa3b, v79
	v_mul_f32_e32 v250, 0xbfb8aa3b, v80
	v_mul_f32_e32 v251, 0xbfb8aa3b, v81
	v_mul_f32_e32 v252, 0xbfb8aa3b, v74
	v_mul_f32_e32 v253, 0xbfb8aa3b, v75
	v_mul_f32_e32 v254, 0xbfb8aa3b, v76
	v_mul_f32_e32 v210, 0xbfb8aa3b, v77
	v_exp_f32_e32 v248, v248
	v_exp_f32_e32 v249, v249
	v_exp_f32_e32 v250, v250
	v_exp_f32_e32 v251, v251
	v_exp_f32_e32 v252, v252
	v_exp_f32_e32 v253, v253
	v_exp_f32_e32 v254, v254
	v_exp_f32_e32 v210, v210
	v_add_f32_e32 v248, 1.0, v248
	v_add_f32_e32 v249, 1.0, v249
	v_add_f32_e32 v250, 1.0, v250
	v_add_f32_e32 v251, 1.0, v251
	v_add_f32_e32 v252, 1.0, v252
	v_add_f32_e32 v253, 1.0, v253
	v_add_f32_e32 v254, 1.0, v254
	v_add_f32_e32 v210, 1.0, v210
	v_rcp_f32_e32 v248, v248
	v_rcp_f32_e32 v249, v249
	v_rcp_f32_e32 v250, v250
	v_rcp_f32_e32 v251, v251
	v_rcp_f32_e32 v252, v252
	v_rcp_f32_e32 v253, v253
	v_rcp_f32_e32 v254, v254
	v_rcp_f32_e32 v210, v210
	v_mul_f32_e32 v78, v78, v248
	v_mul_f32_e32 v79, v79, v249
	v_mul_f32_e32 v80, v80, v250
	v_mul_f32_e32 v81, v81, v251
	v_mul_f32_e32 v74, v74, v252
	v_mul_f32_e32 v75, v75, v253
	v_mul_f32_e32 v76, v76, v254
	v_mul_f32_e32 v77, v77, v210
	s_waitcnt vmcnt(15)
	v_lshlrev_b32_e32 v248, 16, v194
	v_and_b32_e32 v249, 0xffff0000, v194
	v_lshlrev_b32_e32 v250, 16, v195
	v_and_b32_e32 v251, 0xffff0000, v195
	v_lshlrev_b32_e32 v252, 16, v196
	v_and_b32_e32 v253, 0xffff0000, v196
	v_lshlrev_b32_e32 v254, 16, v197
	v_and_b32_e32 v210, 0xffff0000, v197
	v_mul_f32_e32 v78, v78, v248
	v_mul_f32_e32 v79, v79, v249
	v_mul_f32_e32 v80, v80, v250
	v_mul_f32_e32 v81, v81, v251
	v_mul_f32_e32 v74, v74, v252
	v_mul_f32_e32 v75, v75, v253
	v_mul_f32_e32 v76, v76, v254
	v_mul_f32_e32 v77, v77, v210
	v_cvt_pk_bf16_f32 v194, v78, v79
	v_cvt_pk_bf16_f32 v195, v80, v81
	v_cvt_pk_bf16_f32 v196, v74, v75
	v_cvt_pk_bf16_f32 v197, v76, v77
	s_nop 1
	global_store_dwordx4 v137, v[194:197], s[26:27]
	v_mul_f32_e32 v248, 0xbfb8aa3b, v70
	v_mul_f32_e32 v249, 0xbfb8aa3b, v71
	v_mul_f32_e32 v250, 0xbfb8aa3b, v72
	v_mul_f32_e32 v251, 0xbfb8aa3b, v73
	v_mul_f32_e32 v252, 0xbfb8aa3b, v66
	v_mul_f32_e32 v253, 0xbfb8aa3b, v67
	v_mul_f32_e32 v254, 0xbfb8aa3b, v68
	v_mul_f32_e32 v210, 0xbfb8aa3b, v69
	v_exp_f32_e32 v248, v248
	v_exp_f32_e32 v249, v249
	v_exp_f32_e32 v250, v250
	v_exp_f32_e32 v251, v251
	v_exp_f32_e32 v252, v252
	v_exp_f32_e32 v253, v253
	v_exp_f32_e32 v254, v254
	v_exp_f32_e32 v210, v210
	v_add_f32_e32 v248, 1.0, v248
	v_add_f32_e32 v249, 1.0, v249
	v_add_f32_e32 v250, 1.0, v250
	v_add_f32_e32 v251, 1.0, v251
	v_add_f32_e32 v252, 1.0, v252
	v_add_f32_e32 v253, 1.0, v253
	v_add_f32_e32 v254, 1.0, v254
	v_add_f32_e32 v210, 1.0, v210
	v_rcp_f32_e32 v248, v248
	v_rcp_f32_e32 v249, v249
	v_rcp_f32_e32 v250, v250
	v_rcp_f32_e32 v251, v251
	v_rcp_f32_e32 v252, v252
	v_rcp_f32_e32 v253, v253
	v_rcp_f32_e32 v254, v254
	v_rcp_f32_e32 v210, v210
	v_mul_f32_e32 v70, v70, v248
	v_mul_f32_e32 v71, v71, v249
	v_mul_f32_e32 v72, v72, v250
	v_mul_f32_e32 v73, v73, v251
	v_mul_f32_e32 v66, v66, v252
	v_mul_f32_e32 v67, v67, v253
	v_mul_f32_e32 v68, v68, v254
	v_mul_f32_e32 v69, v69, v210
	s_waitcnt vmcnt(15)
	v_lshlrev_b32_e32 v248, 16, v198
	v_and_b32_e32 v249, 0xffff0000, v198
	v_lshlrev_b32_e32 v250, 16, v199
	v_and_b32_e32 v251, 0xffff0000, v199
	v_lshlrev_b32_e32 v252, 16, v200
	v_and_b32_e32 v253, 0xffff0000, v200
	v_lshlrev_b32_e32 v254, 16, v201
	v_and_b32_e32 v210, 0xffff0000, v201
	v_mul_f32_e32 v70, v70, v248
	v_mul_f32_e32 v71, v71, v249
	v_mul_f32_e32 v72, v72, v250
	v_mul_f32_e32 v73, v73, v251
	v_mul_f32_e32 v66, v66, v252
	v_mul_f32_e32 v67, v67, v253
	v_mul_f32_e32 v68, v68, v254
	v_mul_f32_e32 v69, v69, v210
	v_cvt_pk_bf16_f32 v198, v70, v71
	v_cvt_pk_bf16_f32 v199, v72, v73
	v_cvt_pk_bf16_f32 v200, v66, v67
	v_cvt_pk_bf16_f32 v201, v68, v69
	s_nop 1
	global_store_dwordx4 v137, v[198:201], s[26:27] offset:256
	v_mul_f32_e32 v248, 0xbfb8aa3b, v62
	v_mul_f32_e32 v249, 0xbfb8aa3b, v63
	v_mul_f32_e32 v250, 0xbfb8aa3b, v64
	v_mul_f32_e32 v251, 0xbfb8aa3b, v65
	v_mul_f32_e32 v252, 0xbfb8aa3b, v58
	v_mul_f32_e32 v253, 0xbfb8aa3b, v59
	v_mul_f32_e32 v254, 0xbfb8aa3b, v60
	v_mul_f32_e32 v210, 0xbfb8aa3b, v61
	v_exp_f32_e32 v248, v248
	v_exp_f32_e32 v249, v249
	v_exp_f32_e32 v250, v250
	v_exp_f32_e32 v251, v251
	v_exp_f32_e32 v252, v252
	v_exp_f32_e32 v253, v253
	v_exp_f32_e32 v254, v254
	v_exp_f32_e32 v210, v210
	v_add_f32_e32 v248, 1.0, v248
	v_add_f32_e32 v249, 1.0, v249
	v_add_f32_e32 v250, 1.0, v250
	v_add_f32_e32 v251, 1.0, v251
	v_add_f32_e32 v252, 1.0, v252
	v_add_f32_e32 v253, 1.0, v253
	v_add_f32_e32 v254, 1.0, v254
	v_add_f32_e32 v210, 1.0, v210
	v_rcp_f32_e32 v248, v248
	v_rcp_f32_e32 v249, v249
	v_rcp_f32_e32 v250, v250
	v_rcp_f32_e32 v251, v251
	v_rcp_f32_e32 v252, v252
	v_rcp_f32_e32 v253, v253
	v_rcp_f32_e32 v254, v254
	v_rcp_f32_e32 v210, v210
	v_mul_f32_e32 v62, v62, v248
	v_mul_f32_e32 v63, v63, v249
	v_mul_f32_e32 v64, v64, v250
	v_mul_f32_e32 v65, v65, v251
	v_mul_f32_e32 v58, v58, v252
	v_mul_f32_e32 v59, v59, v253
	v_mul_f32_e32 v60, v60, v254
	v_mul_f32_e32 v61, v61, v210
	s_waitcnt vmcnt(15)
	v_lshlrev_b32_e32 v248, 16, v202
	v_and_b32_e32 v249, 0xffff0000, v202
	v_lshlrev_b32_e32 v250, 16, v203
	v_and_b32_e32 v251, 0xffff0000, v203
	v_lshlrev_b32_e32 v252, 16, v204
	v_and_b32_e32 v253, 0xffff0000, v204
	v_lshlrev_b32_e32 v254, 16, v205
	v_and_b32_e32 v210, 0xffff0000, v205
	v_mul_f32_e32 v62, v62, v248
	v_mul_f32_e32 v63, v63, v249
	v_mul_f32_e32 v64, v64, v250
	v_mul_f32_e32 v65, v65, v251
	v_mul_f32_e32 v58, v58, v252
	v_mul_f32_e32 v59, v59, v253
	v_mul_f32_e32 v60, v60, v254
	v_mul_f32_e32 v61, v61, v210
	v_cvt_pk_bf16_f32 v202, v62, v63
	v_cvt_pk_bf16_f32 v203, v64, v65
	v_cvt_pk_bf16_f32 v204, v58, v59
	v_cvt_pk_bf16_f32 v205, v60, v61
	s_nop 1
	global_store_dwordx4 v158, v[202:205], s[26:27]
	v_mul_f32_e32 v248, 0xbfb8aa3b, v54
	v_mul_f32_e32 v249, 0xbfb8aa3b, v55
	v_mul_f32_e32 v250, 0xbfb8aa3b, v56
	v_mul_f32_e32 v251, 0xbfb8aa3b, v57
	v_mul_f32_e32 v252, 0xbfb8aa3b, v50
	v_mul_f32_e32 v253, 0xbfb8aa3b, v51
	v_mul_f32_e32 v254, 0xbfb8aa3b, v52
	v_mul_f32_e32 v210, 0xbfb8aa3b, v53
	v_exp_f32_e32 v248, v248
	v_exp_f32_e32 v249, v249
	v_exp_f32_e32 v250, v250
	v_exp_f32_e32 v251, v251
	v_exp_f32_e32 v252, v252
	v_exp_f32_e32 v253, v253
	v_exp_f32_e32 v254, v254
	v_exp_f32_e32 v210, v210
	v_add_f32_e32 v248, 1.0, v248
	v_add_f32_e32 v249, 1.0, v249
	v_add_f32_e32 v250, 1.0, v250
	v_add_f32_e32 v251, 1.0, v251
	v_add_f32_e32 v252, 1.0, v252
	v_add_f32_e32 v253, 1.0, v253
	v_add_f32_e32 v254, 1.0, v254
	v_add_f32_e32 v210, 1.0, v210
	v_rcp_f32_e32 v248, v248
	v_rcp_f32_e32 v249, v249
	v_rcp_f32_e32 v250, v250
	v_rcp_f32_e32 v251, v251
	v_rcp_f32_e32 v252, v252
	v_rcp_f32_e32 v253, v253
	v_rcp_f32_e32 v254, v254
	v_rcp_f32_e32 v210, v210
	v_mul_f32_e32 v54, v54, v248
	v_mul_f32_e32 v55, v55, v249
	v_mul_f32_e32 v56, v56, v250
	v_mul_f32_e32 v57, v57, v251
	v_mul_f32_e32 v50, v50, v252
	v_mul_f32_e32 v51, v51, v253
	v_mul_f32_e32 v52, v52, v254
	v_mul_f32_e32 v53, v53, v210
	s_waitcnt vmcnt(15)
	v_lshlrev_b32_e32 v248, 16, v206
	v_and_b32_e32 v249, 0xffff0000, v206
	v_lshlrev_b32_e32 v250, 16, v207
	v_and_b32_e32 v251, 0xffff0000, v207
	v_lshlrev_b32_e32 v252, 16, v208
	v_and_b32_e32 v253, 0xffff0000, v208
	v_lshlrev_b32_e32 v254, 16, v209
	v_and_b32_e32 v210, 0xffff0000, v209
	v_mul_f32_e32 v54, v54, v248
	v_mul_f32_e32 v55, v55, v249
	v_mul_f32_e32 v56, v56, v250
	v_mul_f32_e32 v57, v57, v251
	v_mul_f32_e32 v50, v50, v252
	v_mul_f32_e32 v51, v51, v253
	v_mul_f32_e32 v52, v52, v254
	v_mul_f32_e32 v53, v53, v210
	v_cvt_pk_bf16_f32 v206, v54, v55
	v_cvt_pk_bf16_f32 v207, v56, v57
	v_cvt_pk_bf16_f32 v208, v50, v51
	v_cvt_pk_bf16_f32 v209, v52, v53
	s_nop 1
	global_store_dwordx4 v158, v[206:209], s[26:27] offset:256
	v_mul_f32_e32 v248, 0xbfb8aa3b, v46
	v_mul_f32_e32 v249, 0xbfb8aa3b, v47
	v_mul_f32_e32 v250, 0xbfb8aa3b, v48
	v_mul_f32_e32 v251, 0xbfb8aa3b, v49
	v_mul_f32_e32 v252, 0xbfb8aa3b, v42
	v_mul_f32_e32 v253, 0xbfb8aa3b, v43
	v_mul_f32_e32 v254, 0xbfb8aa3b, v44
	v_mul_f32_e32 v210, 0xbfb8aa3b, v45
	v_exp_f32_e32 v248, v248
	v_exp_f32_e32 v249, v249
	v_exp_f32_e32 v250, v250
	v_exp_f32_e32 v251, v251
	v_exp_f32_e32 v252, v252
	v_exp_f32_e32 v253, v253
	v_exp_f32_e32 v254, v254
	v_exp_f32_e32 v210, v210
	v_add_f32_e32 v248, 1.0, v248
	v_add_f32_e32 v249, 1.0, v249
	v_add_f32_e32 v250, 1.0, v250
	v_add_f32_e32 v251, 1.0, v251
	v_add_f32_e32 v252, 1.0, v252
	v_add_f32_e32 v253, 1.0, v253
	v_add_f32_e32 v254, 1.0, v254
	v_add_f32_e32 v210, 1.0, v210
	v_rcp_f32_e32 v248, v248
	v_rcp_f32_e32 v249, v249
	v_rcp_f32_e32 v250, v250
	v_rcp_f32_e32 v251, v251
	v_rcp_f32_e32 v252, v252
	v_rcp_f32_e32 v253, v253
	v_rcp_f32_e32 v254, v254
	v_rcp_f32_e32 v210, v210
	v_mul_f32_e32 v46, v46, v248
	v_mul_f32_e32 v47, v47, v249
	v_mul_f32_e32 v48, v48, v250
	v_mul_f32_e32 v49, v49, v251
	v_mul_f32_e32 v42, v42, v252
	v_mul_f32_e32 v43, v43, v253
	v_mul_f32_e32 v44, v44, v254
	v_mul_f32_e32 v45, v45, v210
	s_waitcnt vmcnt(15)
	v_lshlrev_b32_e32 v248, 16, v224
	v_and_b32_e32 v249, 0xffff0000, v224
	v_lshlrev_b32_e32 v250, 16, v225
	v_and_b32_e32 v251, 0xffff0000, v225
	v_lshlrev_b32_e32 v252, 16, v226
	v_and_b32_e32 v253, 0xffff0000, v226
	v_lshlrev_b32_e32 v254, 16, v227
	v_and_b32_e32 v210, 0xffff0000, v227
	v_mul_f32_e32 v46, v46, v248
	v_mul_f32_e32 v47, v47, v249
	v_mul_f32_e32 v48, v48, v250
	v_mul_f32_e32 v49, v49, v251
	v_mul_f32_e32 v42, v42, v252
	v_mul_f32_e32 v43, v43, v253
	v_mul_f32_e32 v44, v44, v254
	v_mul_f32_e32 v45, v45, v210
	v_cvt_pk_bf16_f32 v224, v46, v47
	v_cvt_pk_bf16_f32 v225, v48, v49
	v_cvt_pk_bf16_f32 v226, v42, v43
	v_cvt_pk_bf16_f32 v227, v44, v45
	s_nop 1
	global_store_dwordx4 v159, v[224:227], s[26:27]
	v_mul_f32_e32 v248, 0xbfb8aa3b, v38
	v_mul_f32_e32 v249, 0xbfb8aa3b, v39
	v_mul_f32_e32 v250, 0xbfb8aa3b, v40
	v_mul_f32_e32 v251, 0xbfb8aa3b, v41
	v_mul_f32_e32 v252, 0xbfb8aa3b, v34
	v_mul_f32_e32 v253, 0xbfb8aa3b, v35
	v_mul_f32_e32 v254, 0xbfb8aa3b, v36
	v_mul_f32_e32 v210, 0xbfb8aa3b, v37
	v_exp_f32_e32 v248, v248
	v_exp_f32_e32 v249, v249
	v_exp_f32_e32 v250, v250
	v_exp_f32_e32 v251, v251
	v_exp_f32_e32 v252, v252
	v_exp_f32_e32 v253, v253
	v_exp_f32_e32 v254, v254
	v_exp_f32_e32 v210, v210
	v_add_f32_e32 v248, 1.0, v248
	v_add_f32_e32 v249, 1.0, v249
	v_add_f32_e32 v250, 1.0, v250
	v_add_f32_e32 v251, 1.0, v251
	v_add_f32_e32 v252, 1.0, v252
	v_add_f32_e32 v253, 1.0, v253
	v_add_f32_e32 v254, 1.0, v254
	v_add_f32_e32 v210, 1.0, v210
	v_rcp_f32_e32 v248, v248
	v_rcp_f32_e32 v249, v249
	v_rcp_f32_e32 v250, v250
	v_rcp_f32_e32 v251, v251
	v_rcp_f32_e32 v252, v252
	v_rcp_f32_e32 v253, v253
	v_rcp_f32_e32 v254, v254
	v_rcp_f32_e32 v210, v210
	v_mul_f32_e32 v38, v38, v248
	v_mul_f32_e32 v39, v39, v249
	v_mul_f32_e32 v40, v40, v250
	v_mul_f32_e32 v41, v41, v251
	v_mul_f32_e32 v34, v34, v252
	v_mul_f32_e32 v35, v35, v253
	v_mul_f32_e32 v36, v36, v254
	v_mul_f32_e32 v37, v37, v210
	s_waitcnt vmcnt(15)
	v_lshlrev_b32_e32 v248, 16, v228
	v_and_b32_e32 v249, 0xffff0000, v228
	v_lshlrev_b32_e32 v250, 16, v229
	v_and_b32_e32 v251, 0xffff0000, v229
	v_lshlrev_b32_e32 v252, 16, v230
	v_and_b32_e32 v253, 0xffff0000, v230
	v_lshlrev_b32_e32 v254, 16, v231
	v_and_b32_e32 v210, 0xffff0000, v231
	v_mul_f32_e32 v38, v38, v248
	v_mul_f32_e32 v39, v39, v249
	v_mul_f32_e32 v40, v40, v250
	v_mul_f32_e32 v41, v41, v251
	v_mul_f32_e32 v34, v34, v252
	v_mul_f32_e32 v35, v35, v253
	v_mul_f32_e32 v36, v36, v254
	v_mul_f32_e32 v37, v37, v210
	v_cvt_pk_bf16_f32 v228, v38, v39
	v_cvt_pk_bf16_f32 v229, v40, v41
	v_cvt_pk_bf16_f32 v230, v34, v35
	v_cvt_pk_bf16_f32 v231, v36, v37
	s_nop 1
	global_store_dwordx4 v159, v[228:231], s[26:27] offset:256
	v_mul_f32_e32 v248, 0xbfb8aa3b, v30
	v_mul_f32_e32 v249, 0xbfb8aa3b, v31
	v_mul_f32_e32 v250, 0xbfb8aa3b, v32
	v_mul_f32_e32 v251, 0xbfb8aa3b, v33
	v_mul_f32_e32 v252, 0xbfb8aa3b, v26
	v_mul_f32_e32 v253, 0xbfb8aa3b, v27
	v_mul_f32_e32 v254, 0xbfb8aa3b, v28
	v_mul_f32_e32 v210, 0xbfb8aa3b, v29
	v_exp_f32_e32 v248, v248
	v_exp_f32_e32 v249, v249
	v_exp_f32_e32 v250, v250
	v_exp_f32_e32 v251, v251
	v_exp_f32_e32 v252, v252
	v_exp_f32_e32 v253, v253
	v_exp_f32_e32 v254, v254
	v_exp_f32_e32 v210, v210
	v_add_f32_e32 v248, 1.0, v248
	v_add_f32_e32 v249, 1.0, v249
	v_add_f32_e32 v250, 1.0, v250
	v_add_f32_e32 v251, 1.0, v251
	v_add_f32_e32 v252, 1.0, v252
	v_add_f32_e32 v253, 1.0, v253
	v_add_f32_e32 v254, 1.0, v254
	v_add_f32_e32 v210, 1.0, v210
	v_rcp_f32_e32 v248, v248
	v_rcp_f32_e32 v249, v249
	v_rcp_f32_e32 v250, v250
	v_rcp_f32_e32 v251, v251
	v_rcp_f32_e32 v252, v252
	v_rcp_f32_e32 v253, v253
	v_rcp_f32_e32 v254, v254
	v_rcp_f32_e32 v210, v210
	v_mul_f32_e32 v30, v30, v248
	v_mul_f32_e32 v31, v31, v249
	v_mul_f32_e32 v32, v32, v250
	v_mul_f32_e32 v33, v33, v251
	v_mul_f32_e32 v26, v26, v252
	v_mul_f32_e32 v27, v27, v253
	v_mul_f32_e32 v28, v28, v254
	v_mul_f32_e32 v29, v29, v210
	s_waitcnt vmcnt(15)
	v_lshlrev_b32_e32 v248, 16, v232
	v_and_b32_e32 v249, 0xffff0000, v232
	v_lshlrev_b32_e32 v250, 16, v233
	v_and_b32_e32 v251, 0xffff0000, v233
	v_lshlrev_b32_e32 v252, 16, v234
	v_and_b32_e32 v253, 0xffff0000, v234
	v_lshlrev_b32_e32 v254, 16, v235
	v_and_b32_e32 v210, 0xffff0000, v235
	v_mul_f32_e32 v30, v30, v248
	v_mul_f32_e32 v31, v31, v249
	v_mul_f32_e32 v32, v32, v250
	v_mul_f32_e32 v33, v33, v251
	v_mul_f32_e32 v26, v26, v252
	v_mul_f32_e32 v27, v27, v253
	v_mul_f32_e32 v28, v28, v254
	v_mul_f32_e32 v29, v29, v210
	v_cvt_pk_bf16_f32 v232, v30, v31
	v_cvt_pk_bf16_f32 v233, v32, v33
	v_cvt_pk_bf16_f32 v234, v26, v27
	v_cvt_pk_bf16_f32 v235, v28, v29
	s_nop 1
	global_store_dwordx4 v160, v[232:235], s[26:27]
	v_mul_f32_e32 v248, 0xbfb8aa3b, v22
	v_mul_f32_e32 v249, 0xbfb8aa3b, v23
	v_mul_f32_e32 v250, 0xbfb8aa3b, v24
	v_mul_f32_e32 v251, 0xbfb8aa3b, v25
	v_mul_f32_e32 v252, 0xbfb8aa3b, v18
	v_mul_f32_e32 v253, 0xbfb8aa3b, v19
	v_mul_f32_e32 v254, 0xbfb8aa3b, v20
	v_mul_f32_e32 v210, 0xbfb8aa3b, v21
	v_exp_f32_e32 v248, v248
	v_exp_f32_e32 v249, v249
	v_exp_f32_e32 v250, v250
	v_exp_f32_e32 v251, v251
	v_exp_f32_e32 v252, v252
	v_exp_f32_e32 v253, v253
	v_exp_f32_e32 v254, v254
	v_exp_f32_e32 v210, v210
	v_add_f32_e32 v248, 1.0, v248
	v_add_f32_e32 v249, 1.0, v249
	v_add_f32_e32 v250, 1.0, v250
	v_add_f32_e32 v251, 1.0, v251
	v_add_f32_e32 v252, 1.0, v252
	v_add_f32_e32 v253, 1.0, v253
	v_add_f32_e32 v254, 1.0, v254
	v_add_f32_e32 v210, 1.0, v210
	v_rcp_f32_e32 v248, v248
	v_rcp_f32_e32 v249, v249
	v_rcp_f32_e32 v250, v250
	v_rcp_f32_e32 v251, v251
	v_rcp_f32_e32 v252, v252
	v_rcp_f32_e32 v253, v253
	v_rcp_f32_e32 v254, v254
	v_rcp_f32_e32 v210, v210
	v_mul_f32_e32 v22, v22, v248
	v_mul_f32_e32 v23, v23, v249
	v_mul_f32_e32 v24, v24, v250
	v_mul_f32_e32 v25, v25, v251
	v_mul_f32_e32 v18, v18, v252
	v_mul_f32_e32 v19, v19, v253
	v_mul_f32_e32 v20, v20, v254
	v_mul_f32_e32 v21, v21, v210
	s_waitcnt vmcnt(15)
	v_lshlrev_b32_e32 v248, 16, v236
	v_and_b32_e32 v249, 0xffff0000, v236
	v_lshlrev_b32_e32 v250, 16, v237
	v_and_b32_e32 v251, 0xffff0000, v237
	v_lshlrev_b32_e32 v252, 16, v238
	v_and_b32_e32 v253, 0xffff0000, v238
	v_lshlrev_b32_e32 v254, 16, v239
	v_and_b32_e32 v210, 0xffff0000, v239
	v_mul_f32_e32 v22, v22, v248
	v_mul_f32_e32 v23, v23, v249
	v_mul_f32_e32 v24, v24, v250
	v_mul_f32_e32 v25, v25, v251
	v_mul_f32_e32 v18, v18, v252
	v_mul_f32_e32 v19, v19, v253
	v_mul_f32_e32 v20, v20, v254
	v_mul_f32_e32 v21, v21, v210
	v_cvt_pk_bf16_f32 v236, v22, v23
	v_cvt_pk_bf16_f32 v237, v24, v25
	v_cvt_pk_bf16_f32 v238, v18, v19
	v_cvt_pk_bf16_f32 v239, v20, v21
	s_nop 1
	global_store_dwordx4 v160, v[236:239], s[26:27] offset:256
	v_mul_f32_e32 v248, 0xbfb8aa3b, v14
	v_mul_f32_e32 v249, 0xbfb8aa3b, v15
	v_mul_f32_e32 v250, 0xbfb8aa3b, v16
	v_mul_f32_e32 v251, 0xbfb8aa3b, v17
	v_mul_f32_e32 v252, 0xbfb8aa3b, v10
	v_mul_f32_e32 v253, 0xbfb8aa3b, v11
	v_mul_f32_e32 v254, 0xbfb8aa3b, v12
	v_mul_f32_e32 v210, 0xbfb8aa3b, v13
	v_exp_f32_e32 v248, v248
	v_exp_f32_e32 v249, v249
	v_exp_f32_e32 v250, v250
	v_exp_f32_e32 v251, v251
	v_exp_f32_e32 v252, v252
	v_exp_f32_e32 v253, v253
	v_exp_f32_e32 v254, v254
	v_exp_f32_e32 v210, v210
	v_add_f32_e32 v248, 1.0, v248
	v_add_f32_e32 v249, 1.0, v249
	v_add_f32_e32 v250, 1.0, v250
	v_add_f32_e32 v251, 1.0, v251
	v_add_f32_e32 v252, 1.0, v252
	v_add_f32_e32 v253, 1.0, v253
	v_add_f32_e32 v254, 1.0, v254
	v_add_f32_e32 v210, 1.0, v210
	v_rcp_f32_e32 v248, v248
	v_rcp_f32_e32 v249, v249
	v_rcp_f32_e32 v250, v250
	v_rcp_f32_e32 v251, v251
	v_rcp_f32_e32 v252, v252
	v_rcp_f32_e32 v253, v253
	v_rcp_f32_e32 v254, v254
	v_rcp_f32_e32 v210, v210
	v_mul_f32_e32 v14, v14, v248
	v_mul_f32_e32 v15, v15, v249
	v_mul_f32_e32 v16, v16, v250
	v_mul_f32_e32 v17, v17, v251
	v_mul_f32_e32 v10, v10, v252
	v_mul_f32_e32 v11, v11, v253
	v_mul_f32_e32 v12, v12, v254
	v_mul_f32_e32 v13, v13, v210
	s_waitcnt vmcnt(15)
	v_lshlrev_b32_e32 v248, 16, v240
	v_and_b32_e32 v249, 0xffff0000, v240
	v_lshlrev_b32_e32 v250, 16, v241
	v_and_b32_e32 v251, 0xffff0000, v241
	v_lshlrev_b32_e32 v252, 16, v242
	v_and_b32_e32 v253, 0xffff0000, v242
	v_lshlrev_b32_e32 v254, 16, v243
	v_and_b32_e32 v210, 0xffff0000, v243
	v_mul_f32_e32 v14, v14, v248
	v_mul_f32_e32 v15, v15, v249
	v_mul_f32_e32 v16, v16, v250
	v_mul_f32_e32 v17, v17, v251
	v_mul_f32_e32 v10, v10, v252
	v_mul_f32_e32 v11, v11, v253
	v_mul_f32_e32 v12, v12, v254
	v_mul_f32_e32 v13, v13, v210
	v_cvt_pk_bf16_f32 v240, v14, v15
	v_cvt_pk_bf16_f32 v241, v16, v17
	v_cvt_pk_bf16_f32 v242, v10, v11
	v_cvt_pk_bf16_f32 v243, v12, v13
	s_nop 1
	global_store_dwordx4 v161, v[240:243], s[26:27]
	v_mul_f32_e32 v248, 0xbfb8aa3b, v6
	v_mul_f32_e32 v249, 0xbfb8aa3b, v7
	v_mul_f32_e32 v250, 0xbfb8aa3b, v8
	v_mul_f32_e32 v251, 0xbfb8aa3b, v9
	v_mul_f32_e32 v252, 0xbfb8aa3b, v2
	v_mul_f32_e32 v253, 0xbfb8aa3b, v3
	v_mul_f32_e32 v254, 0xbfb8aa3b, v4
	v_mul_f32_e32 v210, 0xbfb8aa3b, v5
	v_exp_f32_e32 v248, v248
	v_exp_f32_e32 v249, v249
	v_exp_f32_e32 v250, v250
	v_exp_f32_e32 v251, v251
	v_exp_f32_e32 v252, v252
	v_exp_f32_e32 v253, v253
	v_exp_f32_e32 v254, v254
	v_exp_f32_e32 v210, v210
	v_add_f32_e32 v248, 1.0, v248
	v_add_f32_e32 v249, 1.0, v249
	v_add_f32_e32 v250, 1.0, v250
	v_add_f32_e32 v251, 1.0, v251
	v_add_f32_e32 v252, 1.0, v252
	v_add_f32_e32 v253, 1.0, v253
	v_add_f32_e32 v254, 1.0, v254
	v_add_f32_e32 v210, 1.0, v210
	v_rcp_f32_e32 v248, v248
	v_rcp_f32_e32 v249, v249
	v_rcp_f32_e32 v250, v250
	v_rcp_f32_e32 v251, v251
	v_rcp_f32_e32 v252, v252
	v_rcp_f32_e32 v253, v253
	v_rcp_f32_e32 v254, v254
	v_rcp_f32_e32 v210, v210
	v_mul_f32_e32 v6, v6, v248
	v_mul_f32_e32 v7, v7, v249
	v_mul_f32_e32 v8, v8, v250
	v_mul_f32_e32 v9, v9, v251
	v_mul_f32_e32 v2, v2, v252
	v_mul_f32_e32 v3, v3, v253
	v_mul_f32_e32 v4, v4, v254
	v_mul_f32_e32 v5, v5, v210
	s_waitcnt vmcnt(15)
	v_lshlrev_b32_e32 v248, 16, v244
	v_and_b32_e32 v249, 0xffff0000, v244
	v_lshlrev_b32_e32 v250, 16, v245
	v_and_b32_e32 v251, 0xffff0000, v245
	v_lshlrev_b32_e32 v252, 16, v246
	v_and_b32_e32 v253, 0xffff0000, v246
	v_lshlrev_b32_e32 v254, 16, v247
	v_and_b32_e32 v210, 0xffff0000, v247
	v_mul_f32_e32 v6, v6, v248
	v_mul_f32_e32 v7, v7, v249
	v_mul_f32_e32 v8, v8, v250
	v_mul_f32_e32 v9, v9, v251
	v_mul_f32_e32 v2, v2, v252
	v_mul_f32_e32 v3, v3, v253
	v_mul_f32_e32 v4, v4, v254
	v_mul_f32_e32 v5, v5, v210
	v_cvt_pk_bf16_f32 v244, v6, v7
	v_cvt_pk_bf16_f32 v245, v8, v9
	v_cvt_pk_bf16_f32 v246, v2, v3
	v_cvt_pk_bf16_f32 v247, v4, v5
	s_nop 1
	global_store_dwordx4 v161, v[244:247], s[26:27] offset:256
	s_andn2_b64 vcc, exec, s[4:5]
	s_mov_b64 s[4:5], -1
	s_cbranch_vccnz .LBB0_1455
